# v17_sync2
# speedup vs baseline: 1.0055x; 1.0055x over previous
; __device__ __forceinline__ unsigned xb_ld(unsigned* p)              { return __hip_atomic_load(p, __ATOMIC_RELAXED, __HIP_MEMORY_SCOPE_AGENT); }
; __device__ __forceinline__ unsigned xb_add(unsigned* p, unsigned v) { return __hip_atomic_fetch_add(p, v, __ATOMIC_RELAXED, __HIP_MEMORY_SCOPE_AGENT); }
; #define XB_SPIN(cond, bar) do { unsigned _sp = 0; while (cond) { __builtin_amdgcn_s_sleep(1); \
;     if ((++_sp & 255u) == 0u) { if (xb_ld(&(bar)[XB_TMO])) break; if (_sp > XB_SPIN_CAP) { atomicAdd(&(bar)[XB_TMO], 1u); break; } } } } while (0)
; __device__ __forceinline__ void xcd_barrier(const XcdBarrier& b) {
;     ...
;         const unsigned old = xb_add(&bar[XB_XSUB(b.x)], 1u);
;         const unsigned gen = old / nloc;
;         if (old + 1u == (gen + 1u) * nloc) {
;             __builtin_amdgcn_fence(__ATOMIC_RELEASE, "agent");
;             asm volatile("s_waitcnt vmcnt(0)" ::: "memory");
;             const unsigned og = xb_add(&bar[XB_TOP], 1u);
;             const unsigned tg = og / nx;
;             if (og + 1u == (tg + 1u) * nx) xb_add(&bar[XB_TOPGEN], 1u);
;             else XB_SPIN(xb_ld(&bar[XB_TOPGEN]) == tg, bar);
;             __builtin_amdgcn_fence(__ATOMIC_ACQUIRE, "agent");
;             xb_add(&bar[XB_XGEN(b.x)], 1u);
;             asm volatile("s_waitcnt vmcnt(0)" ::: "memory");
;         } else {
;             XB_SPIN(xb_ld(&bar[XB_XGEN(b.x)]) == gen, bar);
;             __builtin_amdgcn_fence(__ATOMIC_ACQUIRE, "agent");
;             asm volatile("s_waitcnt vmcnt(0)" ::: "memory");
;         }
.LBB0_128:
	s_or_b64 exec, exec, s[14:15]
	v_cvt_f32_u32_e32 v4, v2
	s_waitcnt vmcnt(0)
	v_readfirstlane_b32 s3, v3
	v_sub_u32_e32 v3, 0, v2
	v_rcp_iflag_f32_e32 v4, v4
	v_add_u32_e32 v5, s3, v1
	v_mul_f32_e32 v4, 0x4f7ffffe, v4
	v_cvt_u32_f32_e32 v4, v4
	v_mul_lo_u32 v1, v3, v4
	v_mul_hi_u32 v1, v4, v1
	v_add_u32_e32 v1, v4, v1
	v_mul_hi_u32 v1, v5, v1
	v_mul_lo_u32 v3, v1, v2
	v_sub_u32_e32 v3, v5, v3
	v_add_u32_e32 v4, 1, v1
	v_cmp_ge_u32_e32 vcc, v3, v2
	s_nop 1
	v_cndmask_b32_e32 v1, v1, v4, vcc
	v_sub_u32_e32 v4, v3, v2
	v_cndmask_b32_e32 v3, v3, v4, vcc
	v_add_u32_e32 v4, 1, v1
	v_cmp_ge_u32_e32 vcc, v3, v2
	v_add_u32_e32 v3, 1, v5
	s_nop 0
	v_cndmask_b32_e32 v1, v1, v4, vcc
	v_mul_lo_u32 v4, v2, v1
	v_add_u32_e32 v2, v4, v2
	v_cmp_ne_u32_e32 vcc, v3, v2
	s_and_saveexec_b64 s[6:7], vcc
	s_xor_b64 s[12:13], exec, s[6:7]
	s_cbranch_execz .LBB0_142
	s_waitcnt lgkmcnt(0)
	buffer_inv sc1
	v_cmp_eq_u32_e32 vcc, v5, v4
	s_cbranch_vccz .Lxs_nofirst_0
	buffer_wbl2 sc1
.Lxs_nofirst_0:
	v_mov_b32_e32 v0, 0x2000
	global_load_dword v0, v0, s[10:11] offset:1024 sc1
	s_add_u32 s28, s10, 0x2400
	s_addc_u32 s29, s11, 0
	s_waitcnt vmcnt(0)
	v_cmp_eq_u32_e32 vcc, v0, v1
	s_and_saveexec_b64 s[14:15], vcc
	s_cbranch_execz .LBB0_141
	s_add_u32 s26, s18, 0x30200
	s_addc_u32 s27, s19, 0
	s_mov_b32 s3, 1
	s_mov_b64 s[30:31], 0
	v_mov_b32_e32 v0, 0
	s_branch .LBB0_132

; __device__ __forceinline__ unsigned xb_ld(unsigned* p)              { return __hip_atomic_load(p, __ATOMIC_RELAXED, __HIP_MEMORY_SCOPE_AGENT); }
; __device__ __forceinline__ unsigned xb_add(unsigned* p, unsigned v) { return __hip_atomic_fetch_add(p, v, __ATOMIC_RELAXED, __HIP_MEMORY_SCOPE_AGENT); }
; #define XB_SPIN(cond, bar) do { unsigned _sp = 0; while (cond) { __builtin_amdgcn_s_sleep(1); \
;     if ((++_sp & 255u) == 0u) { if (xb_ld(&(bar)[XB_TMO])) break; if (_sp > XB_SPIN_CAP) { atomicAdd(&(bar)[XB_TMO], 1u); break; } } } } while (0)
; __device__ __forceinline__ void xcd_barrier(const XcdBarrier& b) {
;     ...
;         const unsigned old = xb_add(&bar[XB_XSUB(b.x)], 1u);
;         const unsigned gen = old / nloc;
;         if (old + 1u == (gen + 1u) * nloc) {
;             __builtin_amdgcn_fence(__ATOMIC_RELEASE, "agent");
;             asm volatile("s_waitcnt vmcnt(0)" ::: "memory");
;             const unsigned og = xb_add(&bar[XB_TOP], 1u);
;             const unsigned tg = og / nx;
;             if (og + 1u == (tg + 1u) * nx) xb_add(&bar[XB_TOPGEN], 1u);
;             else XB_SPIN(xb_ld(&bar[XB_TOPGEN]) == tg, bar);
;             __builtin_amdgcn_fence(__ATOMIC_ACQUIRE, "agent");
;             xb_add(&bar[XB_XGEN(b.x)], 1u);
;             asm volatile("s_waitcnt vmcnt(0)" ::: "memory");
;         } else {
;             XB_SPIN(xb_ld(&bar[XB_XGEN(b.x)]) == gen, bar);
;             __builtin_amdgcn_fence(__ATOMIC_ACQUIRE, "agent");
;             asm volatile("s_waitcnt vmcnt(0)" ::: "memory");
;         }
.LBB0_192:
	s_or_b64 exec, exec, s[26:27]
	v_cvt_f32_u32_e32 v4, v2
	s_waitcnt vmcnt(0)
	v_readfirstlane_b32 s3, v3
	v_sub_u32_e32 v3, 0, v2
	v_rcp_iflag_f32_e32 v4, v4
	v_add_u32_e32 v5, s3, v1
	v_mul_f32_e32 v4, 0x4f7ffffe, v4
	v_cvt_u32_f32_e32 v4, v4
	v_mul_lo_u32 v1, v3, v4
	v_mul_hi_u32 v1, v4, v1
	v_add_u32_e32 v1, v4, v1
	v_mul_hi_u32 v1, v5, v1
	v_mul_lo_u32 v3, v1, v2
	v_sub_u32_e32 v3, v5, v3
	v_add_u32_e32 v4, 1, v1
	v_cmp_ge_u32_e32 vcc, v3, v2
	s_nop 1
	v_cndmask_b32_e32 v1, v1, v4, vcc
	v_sub_u32_e32 v4, v3, v2
	v_cndmask_b32_e32 v3, v3, v4, vcc
	v_add_u32_e32 v4, 1, v1
	v_cmp_ge_u32_e32 vcc, v3, v2
	v_add_u32_e32 v3, 1, v5
	s_nop 0
	v_cndmask_b32_e32 v1, v1, v4, vcc
	v_mul_lo_u32 v4, v2, v1
	v_add_u32_e32 v2, v4, v2
	v_cmp_ne_u32_e32 vcc, v3, v2
	s_and_saveexec_b64 s[6:7], vcc
	s_xor_b64 s[12:13], exec, s[6:7]
	s_cbranch_execz .LBB0_206
	s_waitcnt lgkmcnt(0)
	buffer_inv sc1
	v_cmp_eq_u32_e32 vcc, v5, v4
	s_cbranch_vccz .Lxs_nofirst_1
	buffer_wbl2 sc1
.Lxs_nofirst_1:
	v_mov_b32_e32 v0, 0x2000
	global_load_dword v0, v0, s[10:11] offset:1024 sc1
	s_add_u32 s30, s10, 0x2400
	s_addc_u32 s31, s11, 0
	s_waitcnt vmcnt(0)
	v_cmp_eq_u32_e32 vcc, v0, v1
	s_and_saveexec_b64 s[26:27], vcc
	s_cbranch_execz .LBB0_205
	s_add_u32 s28, s18, 0x30200
	s_addc_u32 s29, s19, 0
	s_mov_b32 s3, 1
	s_mov_b64 s[34:35], 0
	v_mov_b32_e32 v0, 0
	s_branch .LBB0_196

; __device__ __forceinline__ unsigned xb_ld(unsigned* p)              { return __hip_atomic_load(p, __ATOMIC_RELAXED, __HIP_MEMORY_SCOPE_AGENT); }
; __device__ __forceinline__ unsigned xb_add(unsigned* p, unsigned v) { return __hip_atomic_fetch_add(p, v, __ATOMIC_RELAXED, __HIP_MEMORY_SCOPE_AGENT); }
; #define XB_SPIN(cond, bar) do { unsigned _sp = 0; while (cond) { __builtin_amdgcn_s_sleep(1); \
;     if ((++_sp & 255u) == 0u) { if (xb_ld(&(bar)[XB_TMO])) break; if (_sp > XB_SPIN_CAP) { atomicAdd(&(bar)[XB_TMO], 1u); break; } } } } while (0)
; __device__ __forceinline__ void xcd_barrier(const XcdBarrier& b) {
;     ...
;         const unsigned old = xb_add(&bar[XB_XSUB(b.x)], 1u);
;         const unsigned gen = old / nloc;
;         if (old + 1u == (gen + 1u) * nloc) {
;             __builtin_amdgcn_fence(__ATOMIC_RELEASE, "agent");
;             asm volatile("s_waitcnt vmcnt(0)" ::: "memory");
;             const unsigned og = xb_add(&bar[XB_TOP], 1u);
;             const unsigned tg = og / nx;
;             if (og + 1u == (tg + 1u) * nx) xb_add(&bar[XB_TOPGEN], 1u);
;             else XB_SPIN(xb_ld(&bar[XB_TOPGEN]) == tg, bar);
;             __builtin_amdgcn_fence(__ATOMIC_ACQUIRE, "agent");
;             xb_add(&bar[XB_XGEN(b.x)], 1u);
;             asm volatile("s_waitcnt vmcnt(0)" ::: "memory");
;         } else {
;             XB_SPIN(xb_ld(&bar[XB_XGEN(b.x)]) == gen, bar);
;             __builtin_amdgcn_fence(__ATOMIC_ACQUIRE, "agent");
;             asm volatile("s_waitcnt vmcnt(0)" ::: "memory");
;         }
.LBB0_268:
	s_or_b64 exec, exec, s[28:29]
	v_cvt_f32_u32_e32 v4, v2
	s_waitcnt vmcnt(0)
	v_readfirstlane_b32 s3, v3
	v_sub_u32_e32 v3, 0, v2
	v_rcp_iflag_f32_e32 v4, v4
	v_add_u32_e32 v5, s3, v1
	v_mul_f32_e32 v4, 0x4f7ffffe, v4
	v_cvt_u32_f32_e32 v4, v4
	v_mul_lo_u32 v1, v3, v4
	v_mul_hi_u32 v1, v4, v1
	v_add_u32_e32 v1, v4, v1
	v_mul_hi_u32 v1, v5, v1
	v_mul_lo_u32 v3, v1, v2
	v_sub_u32_e32 v3, v5, v3
	v_add_u32_e32 v4, 1, v1
	v_cmp_ge_u32_e32 vcc, v3, v2
	s_nop 1
	v_cndmask_b32_e32 v1, v1, v4, vcc
	v_sub_u32_e32 v4, v3, v2
	v_cndmask_b32_e32 v3, v3, v4, vcc
	v_add_u32_e32 v4, 1, v1
	v_cmp_ge_u32_e32 vcc, v3, v2
	v_add_u32_e32 v3, 1, v5
	s_nop 0
	v_cndmask_b32_e32 v1, v1, v4, vcc
	v_mul_lo_u32 v4, v2, v1
	v_add_u32_e32 v2, v4, v2
	v_cmp_ne_u32_e32 vcc, v3, v2
	s_and_saveexec_b64 s[6:7], vcc
	s_xor_b64 s[12:13], exec, s[6:7]
	s_cbranch_execz .LBB0_282
	s_waitcnt lgkmcnt(0)
	buffer_inv sc1
	v_cmp_eq_u32_e32 vcc, v5, v4
	s_cbranch_vccz .Lxs_nofirst_2
	buffer_wbl2 sc1
.Lxs_nofirst_2:
	v_mov_b32_e32 v0, 0x2000
	global_load_dword v0, v0, s[10:11] offset:1024 sc1
	s_add_u32 s34, s10, 0x2400
	s_addc_u32 s35, s11, 0
	s_waitcnt vmcnt(0)
	v_cmp_eq_u32_e32 vcc, v0, v1
	s_and_saveexec_b64 s[28:29], vcc
	s_cbranch_execz .LBB0_281
	s_add_u32 s30, s18, 0x30200
	s_addc_u32 s31, s19, 0
	s_mov_b32 s3, 1
	s_mov_b64 s[36:37], 0
	v_mov_b32_e32 v0, 0
	s_branch .LBB0_272

; __device__ __forceinline__ unsigned xb_ld(unsigned* p)              { return __hip_atomic_load(p, __ATOMIC_RELAXED, __HIP_MEMORY_SCOPE_AGENT); }
; __device__ __forceinline__ unsigned xb_add(unsigned* p, unsigned v) { return __hip_atomic_fetch_add(p, v, __ATOMIC_RELAXED, __HIP_MEMORY_SCOPE_AGENT); }
; #define XB_SPIN(cond, bar) do { unsigned _sp = 0; while (cond) { __builtin_amdgcn_s_sleep(1); \
;     if ((++_sp & 255u) == 0u) { if (xb_ld(&(bar)[XB_TMO])) break; if (_sp > XB_SPIN_CAP) { atomicAdd(&(bar)[XB_TMO], 1u); break; } } } } while (0)
; __device__ __forceinline__ void xcd_barrier(const XcdBarrier& b) {
;     ...
;         const unsigned old = xb_add(&bar[XB_XSUB(b.x)], 1u);
;         const unsigned gen = old / nloc;
;         if (old + 1u == (gen + 1u) * nloc) {
;             __builtin_amdgcn_fence(__ATOMIC_RELEASE, "agent");
;             asm volatile("s_waitcnt vmcnt(0)" ::: "memory");
;             const unsigned og = xb_add(&bar[XB_TOP], 1u);
;             const unsigned tg = og / nx;
;             if (og + 1u == (tg + 1u) * nx) xb_add(&bar[XB_TOPGEN], 1u);
;             else XB_SPIN(xb_ld(&bar[XB_TOPGEN]) == tg, bar);
;             __builtin_amdgcn_fence(__ATOMIC_ACQUIRE, "agent");
;             xb_add(&bar[XB_XGEN(b.x)], 1u);
;             asm volatile("s_waitcnt vmcnt(0)" ::: "memory");
;         } else {
;             XB_SPIN(xb_ld(&bar[XB_XGEN(b.x)]) == gen, bar);
;             __builtin_amdgcn_fence(__ATOMIC_ACQUIRE, "agent");
;             asm volatile("s_waitcnt vmcnt(0)" ::: "memory");
;         }
.LBB0_414:
	s_or_b64 exec, exec, s[28:29]
	v_cvt_f32_u32_e32 v4, v2
	s_waitcnt vmcnt(0)
	v_readfirstlane_b32 s3, v3
	v_sub_u32_e32 v3, 0, v2
	v_rcp_iflag_f32_e32 v4, v4
	v_add_u32_e32 v5, s3, v1
	v_mul_f32_e32 v4, 0x4f7ffffe, v4
	v_cvt_u32_f32_e32 v4, v4
	v_mul_lo_u32 v1, v3, v4
	v_mul_hi_u32 v1, v4, v1
	v_add_u32_e32 v1, v4, v1
	v_mul_hi_u32 v1, v5, v1
	v_mul_lo_u32 v3, v1, v2
	v_sub_u32_e32 v3, v5, v3
	v_add_u32_e32 v4, 1, v1
	v_cmp_ge_u32_e32 vcc, v3, v2
	s_nop 1
	v_cndmask_b32_e32 v1, v1, v4, vcc
	v_sub_u32_e32 v4, v3, v2
	v_cndmask_b32_e32 v3, v3, v4, vcc
	v_add_u32_e32 v4, 1, v1
	v_cmp_ge_u32_e32 vcc, v3, v2
	v_add_u32_e32 v3, 1, v5
	s_nop 0
	v_cndmask_b32_e32 v1, v1, v4, vcc
	v_mul_lo_u32 v4, v2, v1
	v_add_u32_e32 v2, v4, v2
	v_cmp_ne_u32_e32 vcc, v3, v2
	s_and_saveexec_b64 s[6:7], vcc
	s_xor_b64 s[14:15], exec, s[6:7]
	s_cbranch_execz .LBB0_428
	s_waitcnt lgkmcnt(0)
	buffer_inv sc1
	v_cmp_eq_u32_e32 vcc, v5, v4
	s_cbranch_vccz .Lxs_nofirst_4
	buffer_wbl2 sc1
.Lxs_nofirst_4:
	v_mov_b32_e32 v0, 0x2000
	global_load_dword v0, v0, s[12:13] offset:1024 sc1
	s_add_u32 s34, s12, 0x2400
	s_addc_u32 s35, s13, 0
	s_waitcnt vmcnt(0)
	v_cmp_eq_u32_e32 vcc, v0, v1
	s_and_saveexec_b64 s[28:29], vcc
	s_cbranch_execz .LBB0_427
	s_add_u32 s30, s18, 0x30200
	s_addc_u32 s31, s19, 0
	s_mov_b32 s3, 1
	s_mov_b64 s[36:37], 0
	v_mov_b32_e32 v0, 0
	s_branch .LBB0_418

; __device__ __forceinline__ unsigned xb_ld(unsigned* p)              { return __hip_atomic_load(p, __ATOMIC_RELAXED, __HIP_MEMORY_SCOPE_AGENT); }
; __device__ __forceinline__ unsigned xb_add(unsigned* p, unsigned v) { return __hip_atomic_fetch_add(p, v, __ATOMIC_RELAXED, __HIP_MEMORY_SCOPE_AGENT); }
; #define XB_SPIN(cond, bar) do { unsigned _sp = 0; while (cond) { __builtin_amdgcn_s_sleep(1); \
;     if ((++_sp & 255u) == 0u) { if (xb_ld(&(bar)[XB_TMO])) break; if (_sp > XB_SPIN_CAP) { atomicAdd(&(bar)[XB_TMO], 1u); break; } } } } while (0)
; __device__ __forceinline__ void xcd_barrier(const XcdBarrier& b) {
;     ...
;         const unsigned old = xb_add(&bar[XB_XSUB(b.x)], 1u);
;         const unsigned gen = old / nloc;
;         if (old + 1u == (gen + 1u) * nloc) {
;             __builtin_amdgcn_fence(__ATOMIC_RELEASE, "agent");
;             asm volatile("s_waitcnt vmcnt(0)" ::: "memory");
;             const unsigned og = xb_add(&bar[XB_TOP], 1u);
;             const unsigned tg = og / nx;
;             if (og + 1u == (tg + 1u) * nx) xb_add(&bar[XB_TOPGEN], 1u);
;             else XB_SPIN(xb_ld(&bar[XB_TOPGEN]) == tg, bar);
;             __builtin_amdgcn_fence(__ATOMIC_ACQUIRE, "agent");
;             xb_add(&bar[XB_XGEN(b.x)], 1u);
;             asm volatile("s_waitcnt vmcnt(0)" ::: "memory");
;         } else {
;             XB_SPIN(xb_ld(&bar[XB_XGEN(b.x)]) == gen, bar);
;             __builtin_amdgcn_fence(__ATOMIC_ACQUIRE, "agent");
;             asm volatile("s_waitcnt vmcnt(0)" ::: "memory");
;         }
.LBB0_471:
	s_or_b64 exec, exec, s[30:31]
	v_cvt_f32_u32_e32 v4, v2
	s_waitcnt vmcnt(0)
	v_readfirstlane_b32 s3, v3
	v_sub_u32_e32 v3, 0, v2
	v_rcp_iflag_f32_e32 v4, v4
	v_add_u32_e32 v5, s3, v1
	v_mul_f32_e32 v4, 0x4f7ffffe, v4
	v_cvt_u32_f32_e32 v4, v4
	v_mul_lo_u32 v1, v3, v4
	v_mul_hi_u32 v1, v4, v1
	v_add_u32_e32 v1, v4, v1
	v_mul_hi_u32 v1, v5, v1
	v_mul_lo_u32 v3, v1, v2
	v_sub_u32_e32 v3, v5, v3
	v_add_u32_e32 v4, 1, v1
	v_cmp_ge_u32_e32 vcc, v3, v2
	s_nop 1
	v_cndmask_b32_e32 v1, v1, v4, vcc
	v_sub_u32_e32 v4, v3, v2
	v_cndmask_b32_e32 v3, v3, v4, vcc
	v_add_u32_e32 v4, 1, v1
	v_cmp_ge_u32_e32 vcc, v3, v2
	v_add_u32_e32 v3, 1, v5
	s_nop 0
	v_cndmask_b32_e32 v1, v1, v4, vcc
	v_mul_lo_u32 v4, v2, v1
	v_add_u32_e32 v2, v4, v2
	v_cmp_ne_u32_e32 vcc, v3, v2
	s_and_saveexec_b64 s[6:7], vcc
	s_xor_b64 s[28:29], exec, s[6:7]
	s_cbranch_execz .LBB0_485
	s_waitcnt lgkmcnt(0)
	buffer_inv sc1
	v_cmp_eq_u32_e32 vcc, v5, v4
	s_cbranch_vccz .Lxs_nofirst_5
	buffer_wbl2 sc1
.Lxs_nofirst_5:
	v_mov_b32_e32 v0, 0x2000
	global_load_dword v0, v0, s[12:13] offset:1024 sc1
	s_add_u32 s36, s12, 0x2400
	s_addc_u32 s37, s13, 0
	s_waitcnt vmcnt(0)
	v_cmp_eq_u32_e32 vcc, v0, v1
	s_and_saveexec_b64 s[30:31], vcc
	s_cbranch_execz .LBB0_484
	s_add_u32 s34, s18, 0x30200
	s_addc_u32 s35, s19, 0
	s_mov_b32 s3, 1
	s_mov_b64 s[38:39], 0
	v_mov_b32_e32 v0, 0
	s_branch .LBB0_475

; #define KIN(i) karg(i)
; #define KWS(off) ((unsigned char*)karg(26) + (off))
; __device__ __forceinline__ void diff_combine(bf16_t* O0, const bf16_t* O1, const float* sw, float lam, int b, int H, int qb) {
;     ...
;     for (int i = 0; i < 8; ++i) { const int idx = tid + NTHREADS * i, row = idx >> 4, cgp = idx & 15;
;         const size_t off = ((size_t)b * SEQ + (size_t)qb * 256 + row) * 1024 + H * 128 + cgp * 8;
;         const u32x4 a = *(const u32x4*)(O0 + off), c = *(const u32x4*)(O1 + off);
; __global__ void __launch_bounds__(NTHREADS, 2) fwd_megakernel(Args args) {
;     ...
;         __threadfence(); __syncthreads(); __builtin_amdgcn_fence(__ATOMIC_ACQUIRE, "agent"); asm volatile("s_waitcnt vmcnt(0)" ::: "memory");
;         diff_combine((bf16_t*)KWS(WS_O0), (const bf16_t*)KWS(WS_O1), KIN(19), ((const float*)KWS(WS_CONST))[0], b, H, qb);
.LBB0_646:
	s_mov_b64 s[10:11], s[0:1]
	s_waitcnt vmcnt(0)
	s_barrier
	s_waitcnt vmcnt(0)
	s_mov_b64 s[12:13], s[0:1]
	s_load_dwordx2 s[10:11], s[10:11], 0xd0
	s_mov_b64 s[22:23], s[0:1]
	s_load_dwordx2 s[12:13], s[12:13], 0xd0
	s_mov_b64 s[24:25], s[0:1]
	s_load_dwordx2 s[22:23], s[22:23], 0x98
	s_load_dwordx2 s[24:25], s[24:25], 0xd0
	v_mov_b32_e32 v8, v221
	s_waitcnt lgkmcnt(0)
	s_add_u32 s10, s10, 0x8000000
	s_addc_u32 s11, s11, 0
	s_add_u32 s12, s12, 0xa000000
	global_load_dword v2, v213, s[24:25]
	s_mov_b32 s9, 0
	v_lshlrev_b32_e32 v0, 3, v8
	v_and_b32_e32 v0, 0x78, v0
	v_or_b32_e32 v6, s8, v0
	v_lshlrev_b32_e32 v0, 2, v0
	s_addc_u32 s13, s13, 0
	v_lshl_add_u64 v[4:5], s[22:23], 0, v[0:1]
	v_lshlrev_b32_e32 v0, 1, v6
	s_waitcnt vmcnt(0)
	v_mov_b32_e32 v3, v2
	v_xor_b32_e32 v6, 0x80000000, v2

; __device__ __forceinline__ unsigned xb_ld(unsigned* p)              { return __hip_atomic_load(p, __ATOMIC_RELAXED, __HIP_MEMORY_SCOPE_AGENT); }
; __device__ __forceinline__ unsigned xb_add(unsigned* p, unsigned v) { return __hip_atomic_fetch_add(p, v, __ATOMIC_RELAXED, __HIP_MEMORY_SCOPE_AGENT); }
; #define XB_SPIN(cond, bar) do { unsigned _sp = 0; while (cond) { __builtin_amdgcn_s_sleep(1); \
;     if ((++_sp & 255u) == 0u) { if (xb_ld(&(bar)[XB_TMO])) break; if (_sp > XB_SPIN_CAP) { atomicAdd(&(bar)[XB_TMO], 1u); break; } } } } while (0)
; __device__ __forceinline__ void xcd_barrier(const XcdBarrier& b) {
;     ...
;         const unsigned old = xb_add(&bar[XB_XSUB(b.x)], 1u);
;         const unsigned gen = old / nloc;
;         if (old + 1u == (gen + 1u) * nloc) {
;             __builtin_amdgcn_fence(__ATOMIC_RELEASE, "agent");
;             asm volatile("s_waitcnt vmcnt(0)" ::: "memory");
;             const unsigned og = xb_add(&bar[XB_TOP], 1u);
;             const unsigned tg = og / nx;
;             if (og + 1u == (tg + 1u) * nx) xb_add(&bar[XB_TOPGEN], 1u);
;             else XB_SPIN(xb_ld(&bar[XB_TOPGEN]) == tg, bar);
;             __builtin_amdgcn_fence(__ATOMIC_ACQUIRE, "agent");
;             xb_add(&bar[XB_XGEN(b.x)], 1u);
;             asm volatile("s_waitcnt vmcnt(0)" ::: "memory");
;         } else {
;             XB_SPIN(xb_ld(&bar[XB_XGEN(b.x)]) == gen, bar);
;             __builtin_amdgcn_fence(__ATOMIC_ACQUIRE, "agent");
;             asm volatile("s_waitcnt vmcnt(0)" ::: "memory");
;         }
.LBB0_778:
	s_or_b64 exec, exec, s[24:25]
	v_cvt_f32_u32_e32 v4, v2
	s_waitcnt vmcnt(0)
	v_readfirstlane_b32 s3, v3
	v_sub_u32_e32 v3, 0, v2
	v_rcp_iflag_f32_e32 v4, v4
	v_add_u32_e32 v5, s3, v1
	v_mul_f32_e32 v4, 0x4f7ffffe, v4
	v_cvt_u32_f32_e32 v4, v4
	v_mul_lo_u32 v1, v3, v4
	v_mul_hi_u32 v1, v4, v1
	v_add_u32_e32 v1, v4, v1
	v_mul_hi_u32 v1, v5, v1
	v_mul_lo_u32 v3, v1, v2
	v_sub_u32_e32 v3, v5, v3
	v_add_u32_e32 v4, 1, v1
	v_cmp_ge_u32_e32 vcc, v3, v2
	s_nop 1
	v_cndmask_b32_e32 v1, v1, v4, vcc
	v_sub_u32_e32 v4, v3, v2
	v_cndmask_b32_e32 v3, v3, v4, vcc
	v_add_u32_e32 v4, 1, v1
	v_cmp_ge_u32_e32 vcc, v3, v2
	v_add_u32_e32 v3, 1, v5
	s_nop 0
	v_cndmask_b32_e32 v1, v1, v4, vcc
	v_mul_lo_u32 v4, v2, v1
	v_add_u32_e32 v2, v4, v2
	v_cmp_ne_u32_e32 vcc, v3, v2
	s_and_saveexec_b64 s[8:9], vcc
	s_xor_b64 s[14:15], exec, s[8:9]
	s_cbranch_execz .LBB0_792
	s_waitcnt lgkmcnt(0)
	buffer_inv sc1
	v_cmp_eq_u32_e32 vcc, v5, v4
	s_cbranch_vccz .Lxs_nofirst_8
	buffer_wbl2 sc1
.Lxs_nofirst_8:
	v_mov_b32_e32 v0, 0x2000
	global_load_dword v0, v0, s[12:13] offset:1024 sc1
	s_add_u32 s28, s12, 0x2400
	s_addc_u32 s29, s13, 0
	s_waitcnt vmcnt(0)
	v_cmp_eq_u32_e32 vcc, v0, v1
	s_and_saveexec_b64 s[24:25], vcc
	s_cbranch_execz .LBB0_791
	s_add_u32 s26, s18, 0x30200
	s_addc_u32 s27, s19, 0
	s_mov_b32 s3, 1
	s_mov_b64 s[30:31], 0
	v_mov_b32_e32 v0, 0
	s_branch .LBB0_782

; __device__ __forceinline__ unsigned xb_ld(unsigned* p)              { return __hip_atomic_load(p, __ATOMIC_RELAXED, __HIP_MEMORY_SCOPE_AGENT); }
; __device__ __forceinline__ unsigned xb_add(unsigned* p, unsigned v) { return __hip_atomic_fetch_add(p, v, __ATOMIC_RELAXED, __HIP_MEMORY_SCOPE_AGENT); }
; #define XB_SPIN(cond, bar) do { unsigned _sp = 0; while (cond) { __builtin_amdgcn_s_sleep(1); \
;     if ((++_sp & 255u) == 0u) { if (xb_ld(&(bar)[XB_TMO])) break; if (_sp > XB_SPIN_CAP) { atomicAdd(&(bar)[XB_TMO], 1u); break; } } } } while (0)
; __device__ __forceinline__ void xcd_barrier(const XcdBarrier& b) {
;     ...
;         const unsigned old = xb_add(&bar[XB_XSUB(b.x)], 1u);
;         const unsigned gen = old / nloc;
;         if (old + 1u == (gen + 1u) * nloc) {
;             __builtin_amdgcn_fence(__ATOMIC_RELEASE, "agent");
;             asm volatile("s_waitcnt vmcnt(0)" ::: "memory");
;             const unsigned og = xb_add(&bar[XB_TOP], 1u);
;             const unsigned tg = og / nx;
;             if (og + 1u == (tg + 1u) * nx) xb_add(&bar[XB_TOPGEN], 1u);
;             else XB_SPIN(xb_ld(&bar[XB_TOPGEN]) == tg, bar);
;             __builtin_amdgcn_fence(__ATOMIC_ACQUIRE, "agent");
;             xb_add(&bar[XB_XGEN(b.x)], 1u);
;             asm volatile("s_waitcnt vmcnt(0)" ::: "memory");
;         } else {
;             XB_SPIN(xb_ld(&bar[XB_XGEN(b.x)]) == gen, bar);
;             __builtin_amdgcn_fence(__ATOMIC_ACQUIRE, "agent");
;             asm volatile("s_waitcnt vmcnt(0)" ::: "memory");
;         }
.LBB0_904:
	s_or_b64 exec, exec, s[22:23]
	v_cvt_f32_u32_e32 v4, v2
	s_waitcnt vmcnt(0)
	v_readfirstlane_b32 s3, v3
	v_sub_u32_e32 v3, 0, v2
	v_rcp_iflag_f32_e32 v4, v4
	v_add_u32_e32 v5, s3, v1
	v_mul_f32_e32 v4, 0x4f7ffffe, v4
	v_cvt_u32_f32_e32 v4, v4
	v_mul_lo_u32 v1, v3, v4
	v_mul_hi_u32 v1, v4, v1
	v_add_u32_e32 v1, v4, v1
	v_mul_hi_u32 v1, v5, v1
	v_mul_lo_u32 v3, v1, v2
	v_sub_u32_e32 v3, v5, v3
	v_add_u32_e32 v4, 1, v1
	v_cmp_ge_u32_e32 vcc, v3, v2
	s_nop 1
	v_cndmask_b32_e32 v1, v1, v4, vcc
	v_sub_u32_e32 v4, v3, v2
	v_cndmask_b32_e32 v3, v3, v4, vcc
	v_add_u32_e32 v4, 1, v1
	v_cmp_ge_u32_e32 vcc, v3, v2
	v_add_u32_e32 v3, 1, v5
	s_nop 0
	v_cndmask_b32_e32 v1, v1, v4, vcc
	v_mul_lo_u32 v4, v2, v1
	v_add_u32_e32 v2, v4, v2
	v_cmp_ne_u32_e32 vcc, v3, v2
	s_and_saveexec_b64 s[8:9], vcc
	s_xor_b64 s[14:15], exec, s[8:9]
	s_cbranch_execz .LBB0_918
	s_waitcnt lgkmcnt(0)
	buffer_inv sc1
	v_cmp_eq_u32_e32 vcc, v5, v4
	s_cbranch_vccz .Lxs_nofirst_10
	buffer_wbl2 sc1
.Lxs_nofirst_10:
	v_mov_b32_e32 v0, 0x2000
	global_load_dword v0, v0, s[12:13] offset:1024 sc1
	s_add_u32 s26, s12, 0x2400
	s_addc_u32 s27, s13, 0
	s_waitcnt vmcnt(0)
	v_cmp_eq_u32_e32 vcc, v0, v1
	s_and_saveexec_b64 s[22:23], vcc
	s_cbranch_execz .LBB0_917
	s_add_u32 s24, s18, 0x30200
	s_addc_u32 s25, s19, 0
	s_mov_b32 s3, 1
	s_mov_b64 s[28:29], 0
	v_mov_b32_e32 v0, 0
	s_branch .LBB0_908

; __device__ __forceinline__ unsigned xb_ld(unsigned* p)              { return __hip_atomic_load(p, __ATOMIC_RELAXED, __HIP_MEMORY_SCOPE_AGENT); }
; __device__ __forceinline__ unsigned xb_add(unsigned* p, unsigned v) { return __hip_atomic_fetch_add(p, v, __ATOMIC_RELAXED, __HIP_MEMORY_SCOPE_AGENT); }
; #define XB_SPIN(cond, bar) do { unsigned _sp = 0; while (cond) { __builtin_amdgcn_s_sleep(1); \
;     if ((++_sp & 255u) == 0u) { if (xb_ld(&(bar)[XB_TMO])) break; if (_sp > XB_SPIN_CAP) { atomicAdd(&(bar)[XB_TMO], 1u); break; } } } } while (0)
; __device__ __forceinline__ void xcd_barrier(const XcdBarrier& b) {
;     ...
;         const unsigned old = xb_add(&bar[XB_XSUB(b.x)], 1u);
;         const unsigned gen = old / nloc;
;         if (old + 1u == (gen + 1u) * nloc) {
;             __builtin_amdgcn_fence(__ATOMIC_RELEASE, "agent");
;             asm volatile("s_waitcnt vmcnt(0)" ::: "memory");
;             const unsigned og = xb_add(&bar[XB_TOP], 1u);
;             const unsigned tg = og / nx;
;             if (og + 1u == (tg + 1u) * nx) xb_add(&bar[XB_TOPGEN], 1u);
;             else XB_SPIN(xb_ld(&bar[XB_TOPGEN]) == tg, bar);
;             __builtin_amdgcn_fence(__ATOMIC_ACQUIRE, "agent");
;             xb_add(&bar[XB_XGEN(b.x)], 1u);
;             asm volatile("s_waitcnt vmcnt(0)" ::: "memory");
;         } else {
;             XB_SPIN(xb_ld(&bar[XB_XGEN(b.x)]) == gen, bar);
;             __builtin_amdgcn_fence(__ATOMIC_ACQUIRE, "agent");
;             asm volatile("s_waitcnt vmcnt(0)" ::: "memory");
;         }
.LBB0_968:
	s_or_b64 exec, exec, s[12:13]
	v_cvt_f32_u32_e32 v4, v2
	s_waitcnt vmcnt(0)
	v_readfirstlane_b32 s3, v3
	v_sub_u32_e32 v3, 0, v2
	v_rcp_iflag_f32_e32 v4, v4
	v_add_u32_e32 v5, s3, v1
	v_mul_f32_e32 v4, 0x4f7ffffe, v4
	v_cvt_u32_f32_e32 v4, v4
	v_mul_lo_u32 v1, v3, v4
	v_mul_hi_u32 v1, v4, v1
	v_add_u32_e32 v1, v4, v1
	v_mul_hi_u32 v1, v5, v1
	v_mul_lo_u32 v3, v1, v2
	v_sub_u32_e32 v3, v5, v3
	v_add_u32_e32 v4, 1, v1
	v_cmp_ge_u32_e32 vcc, v3, v2
	s_nop 1
	v_cndmask_b32_e32 v1, v1, v4, vcc
	v_sub_u32_e32 v4, v3, v2
	v_cndmask_b32_e32 v3, v3, v4, vcc
	v_add_u32_e32 v4, 1, v1
	v_cmp_ge_u32_e32 vcc, v3, v2
	v_add_u32_e32 v3, 1, v5
	s_nop 0
	v_cndmask_b32_e32 v1, v1, v4, vcc
	v_mul_lo_u32 v4, v2, v1
	v_add_u32_e32 v2, v4, v2
	v_cmp_ne_u32_e32 vcc, v3, v2
	s_and_saveexec_b64 s[10:11], vcc
	s_xor_b64 s[10:11], exec, s[10:11]
	s_cbranch_execz .LBB0_982
	s_waitcnt lgkmcnt(0)
	buffer_inv sc1
	v_cmp_eq_u32_e32 vcc, v5, v4
	s_cbranch_vccz .Lxs_nofirst_11
	buffer_wbl2 sc1
.Lxs_nofirst_11:
	v_mov_b32_e32 v0, 0x2000
	global_load_dword v0, v0, s[4:5] offset:1024 sc1
	s_add_u32 s20, s4, 0x2400
	s_addc_u32 s21, s5, 0
	s_waitcnt vmcnt(0)
	v_cmp_eq_u32_e32 vcc, v0, v1
	s_and_saveexec_b64 s[12:13], vcc
	s_cbranch_execz .LBB0_981
	s_add_u32 s14, s18, 0x30200
	s_addc_u32 s15, s19, 0
	s_mov_b32 s3, 1
	s_mov_b64 s[22:23], 0
	v_mov_b32_e32 v0, 0
	s_branch .LBB0_972
